# hand-scheduled prompt cross-attention unit (K fragments streamed through 8 buffers, V prefetch, deferred-reference softmax) added
# baseline (speedup 1.0000x reference)
; #define LAS __attribute__((address_space(3)))
; #define C_WAITBAR(ahead) do { if ((ahead) >= 2) asm volatile("s_waitcnt vmcnt(8)" ::: "memory"); else if ((ahead) == 1) asm volatile("s_waitcnt vmcnt(4)" ::: "memory"); else asm volatile("s_waitcnt vmcnt(0)" ::: "memory"); \
;         __builtin_amdgcn_s_barrier(); asm volatile("" ::: "memory"); } while (0)
; __device__ __forceinline__ void attnC_dma(const P2Ctx& C, int b, int h, int qblk) {
;     LAS unsigned char* lds = C.lds; const int lane = C.lane, wid = C.wid, pfl = C.pf;
;     const int dvh = wid >> 2, qs = wid & 3, r32 = lane & 31, hi = lane >> 5;
;     const size_t trow0 = (size_t)(b * SEQ + qblk * 128);
;     const size_t qrow = trow0 + qs * 32 + r32;
;     bf16x8 qf[16];
; #pragma unroll
;     for (int ds = 0; ds < 16; ++ds) qf[ds] = *(const bf16x8*)(C.QC + qrow * DM + h * 256 + ds * 16 + hi * 8);
;     const bf16_t* ksrc[2]; const bf16_t* vsrc[2];
; #pragma unroll
;     for (int i = 0; i < 2; ++i) { const int krow = 4 * wid + 2 * i + (lane >> 5), chp = lane & 31, ch = (chp & 16) | ((chp ^ krow) & 15);
;         ksrc[i] = C.MK + ((size_t)(b * 256 + krow)) * DM + h * 256 + ch * 8;
;         const int p = 2 * wid + i, kg = p >> 2, cbv = 2 * (p & 3) + (lane >> 5), vkey = kg * 8 + ((lane >> 2) & 7), vch = cbv * 4 + (lane & 3);
;         vsrc[i] = C.MV + ((size_t)(b * 256 + vkey)) * DM + h * 256 + vch * 8; }
;     ...
;     f32x16 o[4];
; #pragma unroll
;     for (int cb = 0; cb < 4; ++cb)
; #pragma unroll
;         for (int r = 0; r < 16; ++r) o[cb][r] = 0.f;
;     float mhat = 0.f, l = 0.f;
;     f32x16 negm;
; #pragma unroll
;     for (int r = 0; r < 16; ++r) negm[r] = 0.f;
;     C_DMA(0); C_DMA(1); C_DMA(2);
;     C_WAITBAR(2);
; __device__ __forceinline__ void p2_mixers(CArgs& a0, LAS unsigned char* lds, int tid, int lane, int wid, int rep) {
;     ...
;             else if ((it -= 128) < 64) { const int bh = (it >> 4) * 8 + qx; if (umask & 8) attnC_dma(C, bh >> 2, bh & 3, it & 15); }
.LBB0_556:
	s_add_i32 s6, s37, 0xffffff60
	s_and_b32 s10, s6, 15
	s_lshr_b32 s6, s6, 4
	s_lshl_b32 s6, s6, 3
	s_or_b32 s6, s6, s39
	s_lshr_b32 s11, s6, 2
	s_and_b32 s15, s6, 3
	s_lshr_b32 s8, s83, 2
	s_and_b32 s9, s83, 3
	s_mov_b32 s25, 0
	v_and_b32_e32 v164, 31, v219
	v_lshrrev_b32_e32 v165, 5, v219
	s_lshl_b32 s6, s11, 11
	s_lshl_b32 s7, s10, 7
	s_add_i32 s6, s6, s7
	s_lshl_b32 s7, s9, 5
	s_add_i32 s12, s6, s7
	s_lshl_b32 s6, s12, 11
	s_lshl_b32 s7, s15, 9
	s_add_i32 s6, s6, s7
	s_add_u32 s20, s78, 0x10200000
	s_addc_u32 s21, s79, 0
	s_add_u32 s20, s20, s6
	s_addc_u32 s21, s21, 0
	v_lshlrev_b32_e32 v166, 11, v164
	v_lshl_add_u32 v166, v165, 4, v166
	global_load_dwordx4 v[100:103], v166, s[20:21]
	global_load_dwordx4 v[104:107], v166, s[20:21] offset:32
	global_load_dwordx4 v[108:111], v166, s[20:21] offset:64
	global_load_dwordx4 v[112:115], v166, s[20:21] offset:96
	global_load_dwordx4 v[116:119], v166, s[20:21] offset:128
	global_load_dwordx4 v[120:123], v166, s[20:21] offset:160
	global_load_dwordx4 v[124:127], v166, s[20:21] offset:192
	global_load_dwordx4 v[128:131], v166, s[20:21] offset:224
	global_load_dwordx4 v[132:135], v166, s[20:21] offset:256
	global_load_dwordx4 v[136:139], v166, s[20:21] offset:288
	global_load_dwordx4 v[140:143], v166, s[20:21] offset:320
	global_load_dwordx4 v[144:147], v166, s[20:21] offset:352
	global_load_dwordx4 v[148:151], v166, s[20:21] offset:384
	global_load_dwordx4 v[152:155], v166, s[20:21] offset:416
	global_load_dwordx4 v[156:159], v166, s[20:21] offset:448
	global_load_dwordx4 v[160:163], v166, s[20:21] offset:480
	s_lshl_b32 s7, s8, 8
	s_add_i32 s6, s6, s7
	s_add_u32 s22, s78, 0x1c800000
	s_addc_u32 s23, s79, 0
	s_add_u32 s22, s22, s6
	s_addc_u32 s23, s23, 0
	s_lshl_b32 s6, s11, 19
	s_lshl_b32 s7, s15, 9
	s_add_i32 s6, s6, s7
	s_add_u32 s16, s78, 0x5500000
	s_addc_u32 s17, s79, 0
	s_add_u32 s16, s16, s6
	s_addc_u32 s17, s17, 0
	s_add_u32 s18, s78, 0x5900000
	s_addc_u32 s19, s79, 0
	s_add_u32 s18, s18, s6
	s_addc_u32 s19, s19, 0
	s_mov_b32 s24, 0
	s_lshl_b32 s13, s83, 11
	s_lshl_b32 s6, s83, 2
	v_add_u32_e32 v167, s6, v165
	v_and_b32_e32 v168, 31, v219
	v_xor_b32_e32 v169, v168, v167
	v_and_b32_e32 v169, 15, v169
	v_and_b32_e32 v168, 16, v168
	v_or_b32_e32 v168, v168, v169
	v_lshlrev_b32_e32 v168, 4, v168
	v_lshl_add_u32 v197, v167, 11, v168
	s_lshl_b32 s6, s83, 2
	s_add_i32 s6, s6, 2
	v_add_u32_e32 v167, s6, v165
	v_and_b32_e32 v168, 31, v219
	v_xor_b32_e32 v169, v168, v167
	v_and_b32_e32 v169, 15, v169
	v_and_b32_e32 v168, 16, v168
	v_or_b32_e32 v168, v168, v169
	v_lshlrev_b32_e32 v168, 4, v168
	v_lshl_add_u32 v198, v167, 11, v168
	s_lshr_b32 s6, s83, 1
	s_lshl_b32 s6, s6, 3
	v_bfe_u32 v167, v219, 2, 3
	v_add_u32_e32 v167, s6, v167
	s_and_b32 s6, s83, 1
	s_lshl_b32 s6, s6, 2
	v_add_u32_e32 v168, s6, v165
	v_lshlrev_b32_e32 v168, 6, v168
	v_and_b32_e32 v169, 3, v219
	v_lshl_add_u32 v168, v169, 4, v168
	v_lshl_add_u32 v200, v167, 11, v168
	s_and_b32 s6, s24, 3
	s_lshl_b32 s6, s6, 15
	s_add_i32 s7, s6, s13
	s_mov_b32 m0, s7
	s_add_u32 s20, s18, 0x80
	s_addc_u32 s21, s19, 0
	s_add_i32 s24, s24, 1
	global_load_lds_dwordx4 v197, s[16:17]
	s_add_i32 m0, s7, 0x400
	s_add_i32 s7, s7, 0x4000
	s_nop 0
	s_nop 0
	global_load_lds_dwordx4 v198, s[16:17]
	s_mov_b32 m0, s7
	s_add_u32 s16, s16, 0x10000
	s_addc_u32 s17, s17, 0
	s_nop 0
	global_load_lds_dwordx4 v200, s[18:19]
	s_add_i32 m0, s7, 0x400
	s_add_u32 s18, s18, 0x10000
	s_addc_u32 s19, s19, 0
	s_nop 0
	global_load_lds_dwordx4 v200, s[20:21]
	s_and_b32 s6, s24, 3
	s_lshl_b32 s6, s6, 15
	s_add_i32 s7, s6, s13
	s_mov_b32 m0, s7
	s_add_u32 s20, s18, 0x80
	s_addc_u32 s21, s19, 0
	s_add_i32 s24, s24, 1
	global_load_lds_dwordx4 v197, s[16:17]
	s_add_i32 m0, s7, 0x400
	s_add_i32 s7, s7, 0x4000
	s_nop 0
	s_nop 0
	global_load_lds_dwordx4 v198, s[16:17]
	s_mov_b32 m0, s7
	s_add_u32 s16, s16, 0x10000
	s_addc_u32 s17, s17, 0
	s_nop 0
	global_load_lds_dwordx4 v200, s[18:19]
	s_add_i32 m0, s7, 0x400
	s_add_u32 s18, s18, 0x10000
	s_addc_u32 s19, s19, 0
	s_nop 0
	global_load_lds_dwordx4 v200, s[20:21]
	s_and_b32 s6, s24, 3
	s_lshl_b32 s6, s6, 15
	s_add_i32 s7, s6, s13
	s_mov_b32 m0, s7
	s_add_u32 s20, s18, 0x80
	s_addc_u32 s21, s19, 0
	s_add_i32 s24, s24, 1
	global_load_lds_dwordx4 v197, s[16:17]
	s_add_i32 m0, s7, 0x400
	s_add_i32 s7, s7, 0x4000
	s_nop 0
	s_nop 0
	global_load_lds_dwordx4 v198, s[16:17]
	s_mov_b32 m0, s7
	s_add_u32 s16, s16, 0x10000
	s_addc_u32 s17, s17, 0
	s_nop 0
	global_load_lds_dwordx4 v200, s[18:19]
	s_add_i32 m0, s7, 0x400
	s_add_u32 s18, s18, 0x10000
	s_addc_u32 s19, s19, 0
	s_nop 0
	global_load_lds_dwordx4 v200, s[20:21]
	v_and_b32_e32 v167, 15, v164
	v_xor_b32_e32 v167, v167, v165
	v_lshlrev_b32_e32 v167, 4, v167
	v_lshl_add_u32 v201, v164, 9, v167
	v_bfe_u32 v167, v219, 2, 2
	v_lshl_add_u32 v167, v165, 2, v167
	v_lshlrev_b32_e32 v167, 6, v167
	v_bfe_u32 v168, v219, 4, 1
	v_lshl_add_u32 v167, v168, 5, v167
	v_and_b32_e32 v168, 3, v219
	v_lshl_add_u32 v167, v168, 3, v167
	s_lshl_b32 s6, s8, 11
	s_add_i32 s6, s6, 0x4000
	v_add_u32_e32 v202, s6, v167
	v_mov_b32_e32 v4, 0
	v_mov_b32_e32 v5, 0
	v_mov_b32_e32 v6, 0
	v_mov_b32_e32 v7, 0
	v_mov_b32_e32 v8, 0
	v_mov_b32_e32 v9, 0
	v_mov_b32_e32 v10, 0
	v_mov_b32_e32 v11, 0
	v_mov_b32_e32 v12, 0
	v_mov_b32_e32 v13, 0
	v_mov_b32_e32 v14, 0
	v_mov_b32_e32 v15, 0
	v_mov_b32_e32 v16, 0
	v_mov_b32_e32 v17, 0
	v_mov_b32_e32 v18, 0
	v_mov_b32_e32 v19, 0
	v_mov_b32_e32 v20, 0
	v_mov_b32_e32 v21, 0
	v_mov_b32_e32 v22, 0
	v_mov_b32_e32 v23, 0
	v_mov_b32_e32 v24, 0
	v_mov_b32_e32 v25, 0
	v_mov_b32_e32 v26, 0
	v_mov_b32_e32 v27, 0
	v_mov_b32_e32 v28, 0
	v_mov_b32_e32 v29, 0
	v_mov_b32_e32 v30, 0
	v_mov_b32_e32 v31, 0
	v_mov_b32_e32 v32, 0
	v_mov_b32_e32 v33, 0
	v_mov_b32_e32 v34, 0
	v_mov_b32_e32 v35, 0
	v_mov_b32_e32 v36, 0
	v_mov_b32_e32 v37, 0
	v_mov_b32_e32 v38, 0
	v_mov_b32_e32 v39, 0
	v_mov_b32_e32 v40, 0
	v_mov_b32_e32 v41, 0
	v_mov_b32_e32 v42, 0
	v_mov_b32_e32 v43, 0
	v_mov_b32_e32 v44, 0
	v_mov_b32_e32 v45, 0
	v_mov_b32_e32 v46, 0
	v_mov_b32_e32 v47, 0
	v_mov_b32_e32 v48, 0
	v_mov_b32_e32 v49, 0
	v_mov_b32_e32 v50, 0
	v_mov_b32_e32 v51, 0
	v_mov_b32_e32 v52, 0
	v_mov_b32_e32 v53, 0
	v_mov_b32_e32 v54, 0
	v_mov_b32_e32 v55, 0
	v_mov_b32_e32 v56, 0
	v_mov_b32_e32 v57, 0
	v_mov_b32_e32 v58, 0
	v_mov_b32_e32 v59, 0
	v_mov_b32_e32 v60, 0
	v_mov_b32_e32 v61, 0
	v_mov_b32_e32 v62, 0
	v_mov_b32_e32 v63, 0
	v_mov_b32_e32 v64, 0
	v_mov_b32_e32 v65, 0
	v_mov_b32_e32 v66, 0
	v_mov_b32_e32 v67, 0
	v_mov_b32_e32 v220, 0
	v_mov_b32_e32 v221, 0
	v_mov_b32_e32 v222, 0
	v_mov_b32_e32 v223, 0
	v_mov_b32_e32 v224, 0
	v_mov_b32_e32 v225, 0
	v_mov_b32_e32 v226, 0
	v_mov_b32_e32 v227, 0
	v_mov_b32_e32 v228, 0
	v_mov_b32_e32 v229, 0
	v_mov_b32_e32 v230, 0
	v_mov_b32_e32 v231, 0
	v_mov_b32_e32 v232, 0
	v_mov_b32_e32 v233, 0
	v_mov_b32_e32 v234, 0
	v_mov_b32_e32 v235, 0
	v_mov_b32_e32 v203, 0
	v_mov_b32_e32 v204, 0
	s_mov_b32 s14, 0
	s_waitcnt vmcnt(8)
	s_barrier
; #define LAS __attribute__((address_space(3)))
; __device__ __forceinline__ void attnC_dma(const P2Ctx& C, int b, int h, int qblk) {
;     ...
;     for (int kt = 0; kt < 8; ++kt) {
;         if (kt + 3 < 8 && !(pfl & 16)) C_DMA(kt + 3);
;         const LAS unsigned char* sb = lds + (kt & 3) * 32768;
;         f32x16 s = negm;
;         if (!(pfl & 8)) {
; #pragma unroll
;         for (int ds = 0; ds < 16; ++ds) { const int ch = 2 * ds + hi;
;             const bf16x8 kf = *(const LAS bf16x8*)(sb + r32 * 512 + (((ch & 16) | ((ch ^ r32) & 15)) << 4));
;             s = MFMA32(kf, qf[ds], ds == 0 ? negm : s); } }
;         bf16x8 p0 = (bf16x8){0,0,0,0,0,0,0,0}, p1 = p0;
;         if (!(pfl & 4)) {
;         float mx = s[0];
; #pragma unroll
;         for (int r = 1; r < 16; ++r) mx = fmaxf(mx, s[r]);
;         mx = fmaxf(mx, __shfl_xor(mx, 32));
;         if (kt == 0 || __any(mx > ATHR)) {
;             const float dl = kt == 0 ? mx : fmaxf(mx, 0.f);
;             mhat += dl;
; #pragma unroll
;             for (int r = 0; r < 16; ++r) negm[r] = -mhat;
;             const float f = kt == 0 ? 1.0f : fexp2(-dl); l *= f;
; #pragma unroll
;             for (int r = 0; r < 16; ++r) s[r] -= dl;
; #pragma unroll
;             for (int cb = 0; cb < 4; ++cb)
; #pragma unroll
;                 for (int r = 0; r < 16; ++r) o[cb][r] *= f;
;         }
;         float ps = 0.f;
; #pragma unroll
;         for (int r = 0; r < 16; ++r) { const float p = fexp2(s[r]); s[r] = p; ps += p; }
;         l += ps;
;         p0 = pack_p(s, 0); p1 = pack_p(s, 1); }
;         if (!(pfl & 2)) { const LAS unsigned char* vimg = sb + 16384; VRaw va, vb;
;           v_issue2<8>(vimg, dvh * 4 + 0, lane, va); v_wait2(va);
;           v_issue2<8>(vimg, dvh * 4 + 1, lane, vb); __builtin_amdgcn_sched_barrier(0);
;           o[0] = MFMA32(v_build(va, 0), p0, o[0]); o[0] = MFMA32(v_build(va, 1), p1, o[0]); __builtin_amdgcn_sched_barrier(0); v_wait2(vb);
;           v_issue2<8>(vimg, dvh * 4 + 2, lane, va); __builtin_amdgcn_sched_barrier(0);
;           o[1] = MFMA32(v_build(vb, 0), p0, o[1]); o[1] = MFMA32(v_build(vb, 1), p1, o[1]); __builtin_amdgcn_sched_barrier(0); v_wait2(va);
;           v_issue2<8>(vimg, dvh * 4 + 3, lane, vb); __builtin_amdgcn_sched_barrier(0);
;           o[2] = MFMA32(v_build(va, 0), p0, o[2]); o[2] = MFMA32(v_build(va, 1), p1, o[2]); __builtin_amdgcn_sched_barrier(0); v_wait2(vb);
.LcC_loop:
	s_cmp_lt_u32 s24, 8
	s_cbranch_scc0 .LcC_nodma_1
	s_and_b32 s6, s24, 3
	s_lshl_b32 s6, s6, 15
	s_add_i32 s7, s6, s13
	s_mov_b32 m0, s7
	s_add_u32 s20, s18, 0x80
	s_addc_u32 s21, s19, 0
	s_add_i32 s24, s24, 1
	global_load_lds_dwordx4 v197, s[16:17]
	s_add_i32 m0, s7, 0x400
	s_add_i32 s7, s7, 0x4000
	s_nop 0
	s_nop 0
	global_load_lds_dwordx4 v198, s[16:17]
	s_mov_b32 m0, s7
	s_add_u32 s16, s16, 0x10000
	s_addc_u32 s17, s17, 0
	s_nop 0
	global_load_lds_dwordx4 v200, s[18:19]
	s_add_i32 m0, s7, 0x400
	s_add_u32 s18, s18, 0x10000
	s_addc_u32 s19, s19, 0
	s_nop 0
	global_load_lds_dwordx4 v200, s[20:21]
.LcC_nodma_1:
	s_and_b32 s6, s14, 3
	s_lshl_b32 s6, s6, 15
	v_add_u32_e32 v250, s6, v201
	v_add_u32_e32 v251, s6, v202
	ds_read_b128 v[164:167], v250
	v_xor_b32_e32 v2, 0x20, v250
	ds_read_b128 v[168:171], v2
	v_xor_b32_e32 v2, 0x40, v250
	ds_read_b128 v[172:175], v2
	v_xor_b32_e32 v2, 0x60, v250
	ds_read_b128 v[176:179], v2
	v_xor_b32_e32 v2, 0x80, v250
	ds_read_b128 v[180:183], v2
	v_xor_b32_e32 v2, 0xa0, v250
	ds_read_b128 v[184:187], v2
	v_xor_b32_e32 v2, 0xc0, v250
	ds_read_b128 v[188:191], v2
	v_xor_b32_e32 v2, 0xe0, v250
	ds_read_b128 v[192:195], v2
	s_waitcnt lgkmcnt(7)
	v_mfma_f32_32x32x16_bf16 v[68:83], v[164:167], v[100:103], v[220:235]
	ds_read_b128 v[164:167], v250 offset:256
	s_waitcnt lgkmcnt(7)
	v_mfma_f32_32x32x16_bf16 v[68:83], v[168:171], v[104:107], v[68:83]
	v_xor_b32_e32 v2, 0x20, v250
	ds_read_b128 v[168:171], v2 offset:256
	s_waitcnt lgkmcnt(7)
	v_mfma_f32_32x32x16_bf16 v[68:83], v[172:175], v[108:111], v[68:83]
	v_xor_b32_e32 v2, 0x40, v250
	ds_read_b128 v[172:175], v2 offset:256
	s_waitcnt lgkmcnt(7)
	v_mfma_f32_32x32x16_bf16 v[68:83], v[176:179], v[112:115], v[68:83]
	v_xor_b32_e32 v2, 0x60, v250
	ds_read_b128 v[176:179], v2 offset:256
	s_waitcnt lgkmcnt(7)
	v_mfma_f32_32x32x16_bf16 v[68:83], v[180:183], v[116:119], v[68:83]
	v_xor_b32_e32 v2, 0x80, v250
	ds_read_b128 v[180:183], v2 offset:256
	s_waitcnt lgkmcnt(7)
	v_mfma_f32_32x32x16_bf16 v[68:83], v[184:187], v[120:123], v[68:83]
	v_xor_b32_e32 v2, 0xa0, v250
	ds_read_b128 v[184:187], v2 offset:256
	s_waitcnt lgkmcnt(7)
	v_mfma_f32_32x32x16_bf16 v[68:83], v[188:191], v[124:127], v[68:83]
	v_xor_b32_e32 v2, 0xc0, v250
	ds_read_b128 v[188:191], v2 offset:256
	s_waitcnt lgkmcnt(7)
	v_mfma_f32_32x32x16_bf16 v[68:83], v[192:195], v[128:131], v[68:83]
	v_xor_b32_e32 v2, 0xe0, v250
	ds_read_b128 v[192:195], v2 offset:256
	s_waitcnt lgkmcnt(7)
	v_mfma_f32_32x32x16_bf16 v[68:83], v[164:167], v[132:135], v[68:83]
	s_waitcnt lgkmcnt(6)
	v_mfma_f32_32x32x16_bf16 v[68:83], v[168:171], v[136:139], v[68:83]
	s_waitcnt lgkmcnt(5)
	v_mfma_f32_32x32x16_bf16 v[68:83], v[172:175], v[140:143], v[68:83]
	s_waitcnt lgkmcnt(4)
	v_mfma_f32_32x32x16_bf16 v[68:83], v[176:179], v[144:147], v[68:83]
	s_waitcnt lgkmcnt(3)
	v_mfma_f32_32x32x16_bf16 v[68:83], v[180:183], v[148:151], v[68:83]
	s_waitcnt lgkmcnt(2)
	v_mfma_f32_32x32x16_bf16 v[68:83], v[184:187], v[152:155], v[68:83]
	s_waitcnt lgkmcnt(1)
	v_mfma_f32_32x32x16_bf16 v[68:83], v[188:191], v[156:159], v[68:83]
	s_waitcnt lgkmcnt(0)
	v_mfma_f32_32x32x16_bf16 v[68:83], v[192:195], v[160:163], v[68:83]
	ds_read_b64_tr_b16 v[84:85], v251 offset:0
	ds_read_b64_tr_b16 v[86:87], v251 offset:4096
	ds_read_b64_tr_b16 v[88:89], v251 offset:8192
	ds_read_b64_tr_b16 v[90:91], v251 offset:12288
	s_nop 7
	s_nop 3
	v_max3_f32 v236, v68, v69, v70
	v_max3_f32 v236, v236, v71, v72
	v_max3_f32 v236, v236, v73, v74
	v_max3_f32 v236, v236, v75, v76
	v_max3_f32 v236, v236, v77, v78
	v_max3_f32 v236, v236, v79, v80
	v_max3_f32 v236, v236, v81, v82
	v_max_f32_e32 v236, v236, v83
	v_mov_b32_e32 v237, v236
	s_nop 1
	v_permlane32_swap_b32 v237, v236
	v_max_f32_e32 v248, v237, v236
	s_cmp_eq_u32 s14, 0
	s_cbranch_scc1 .LcC_first
	v_cmp_lt_f32_e32 vcc, 0x41000000, v248
	s_cmp_lg_u64 vcc, 0
	s_cbranch_scc1 .LcC_resc
.LcC_back:
	v_exp_f32_e32 v68, v68
	v_exp_f32_e32 v69, v69
	v_exp_f32_e32 v70, v70
	v_exp_f32_e32 v71, v71
	v_exp_f32_e32 v72, v72
	v_exp_f32_e32 v73, v73
	v_exp_f32_e32 v74, v74
	v_exp_f32_e32 v75, v75
	v_exp_f32_e32 v76, v76
	v_exp_f32_e32 v77, v77
	v_exp_f32_e32 v78, v78
	v_exp_f32_e32 v79, v79
	v_exp_f32_e32 v80, v80
	v_exp_f32_e32 v81, v81
	v_exp_f32_e32 v82, v82
	v_exp_f32_e32 v83, v83
	v_add_f32_e32 v236, v68, v69
	v_add_f32_e32 v237, v70, v71
	v_add_f32_e32 v236, v236, v72
	v_add_f32_e32 v237, v237, v73
	v_add_f32_e32 v236, v236, v74
	v_add_f32_e32 v237, v237, v75
	v_add_f32_e32 v236, v236, v76
	v_add_f32_e32 v237, v237, v77
	v_add_f32_e32 v236, v236, v78
	v_add_f32_e32 v237, v237, v79
	v_add_f32_e32 v236, v236, v80
	v_add_f32_e32 v237, v237, v81
	v_add_f32_e32 v236, v236, v82
	v_add_f32_e32 v237, v237, v83
	v_add_f32_e32 v236, v236, v237
	v_add_f32_e32 v204, v204, v236
	v_cvt_pk_bf16_f32 v240, v68, v69
	v_cvt_pk_bf16_f32 v241, v70, v71
	v_cvt_pk_bf16_f32 v242, v72, v73
	v_cvt_pk_bf16_f32 v243, v74, v75
	v_cvt_pk_bf16_f32 v244, v76, v77
	v_cvt_pk_bf16_f32 v245, v78, v79
	v_cvt_pk_bf16_f32 v246, v80, v81
	v_cvt_pk_bf16_f32 v247, v82, v83
	s_waitcnt lgkmcnt(0)
	ds_read_b64_tr_b16 v[92:93], v251 offset:512
	ds_read_b64_tr_b16 v[94:95], v251 offset:4608
	ds_read_b64_tr_b16 v[96:97], v251 offset:8704
	ds_read_b64_tr_b16 v[98:99], v251 offset:12800
	v_mfma_f32_32x32x16_bf16 v[4:19], v[84:87], v[240:243], v[4:19]
	v_mfma_f32_32x32x16_bf16 v[4:19], v[88:91], v[244:247], v[4:19]
	s_waitcnt lgkmcnt(0)
	ds_read_b64_tr_b16 v[84:85], v251 offset:1024
	ds_read_b64_tr_b16 v[86:87], v251 offset:5120
	ds_read_b64_tr_b16 v[88:89], v251 offset:9216
	ds_read_b64_tr_b16 v[90:91], v251 offset:13312
	v_mfma_f32_32x32x16_bf16 v[20:35], v[92:95], v[240:243], v[20:35]
	v_mfma_f32_32x32x16_bf16 v[20:35], v[96:99], v[244:247], v[20:35]
	s_waitcnt lgkmcnt(0)
	ds_read_b64_tr_b16 v[92:93], v251 offset:1536
	ds_read_b64_tr_b16 v[94:95], v251 offset:5632
	ds_read_b64_tr_b16 v[96:97], v251 offset:9728
	ds_read_b64_tr_b16 v[98:99], v251 offset:13824
	v_mfma_f32_32x32x16_bf16 v[36:51], v[84:87], v[240:243], v[36:51]
	v_mfma_f32_32x32x16_bf16 v[36:51], v[88:91], v[244:247], v[36:51]
	s_waitcnt lgkmcnt(0)
	v_mfma_f32_32x32x16_bf16 v[52:67], v[92:95], v[240:243], v[52:67]
	v_mfma_f32_32x32x16_bf16 v[52:67], v[96:99], v[244:247], v[52:67]
	s_add_i32 s6, s14, 3
	s_cmp_lt_u32 s6, 8
	s_cbranch_scc1 .LcC_w8_2
	s_add_i32 s6, s14, 2
	s_cmp_lt_u32 s6, 8
	s_cbranch_scc1 .LcC_w4_3
	s_waitcnt vmcnt(0)
	s_branch .LcC_wd_4
.LcC_w8_2:
	s_waitcnt vmcnt(8)
	s_branch .LcC_wd_4

; __device__ __forceinline__ float fexp2(float x) { return __builtin_amdgcn_exp2f(x); }
; #define C_WAITBAR(ahead) do { if ((ahead) >= 2) asm volatile("s_waitcnt vmcnt(8)" ::: "memory"); else if ((ahead) == 1) asm volatile("s_waitcnt vmcnt(4)" ::: "memory"); else asm volatile("s_waitcnt vmcnt(0)" ::: "memory"); \
;         __builtin_amdgcn_s_barrier(); asm volatile("" ::: "memory"); } while (0)
; __device__ __forceinline__ void attnC_dma(const P2Ctx& C, int b, int h, int qblk) {
;     ...
;         if (kt == 0 || __any(mx > ATHR)) {
;             const float dl = kt == 0 ? mx : fmaxf(mx, 0.f);
;             mhat += dl;
; #pragma unroll
;             for (int r = 0; r < 16; ++r) negm[r] = -mhat;
;             const float f = kt == 0 ? 1.0f : fexp2(-dl); l *= f;
; #pragma unroll
;             for (int r = 0; r < 16; ++r) s[r] -= dl;
; #pragma unroll
;             for (int cb = 0; cb < 4; ++cb)
; #pragma unroll
;                 for (int r = 0; r < 16; ++r) o[cb][r] *= f;
;         }
;     ...
;         { const int lastt = 7 < kt + 3 ? 7 : kt + 3; const int ahead = lastt - (kt + 1); C_WAITBAR(ahead); }
;     }
.LcC_wd_4:
	s_barrier
	s_add_i32 s14, s14, 1
	s_cmp_lt_u32 s14, 8
	s_cbranch_scc1 .LcC_loop
	s_branch .LcC_epi
.LcC_first:
	v_mov_b32_e32 v203, v248
	v_sub_f32_e32 v68, v68, v248
	v_sub_f32_e32 v69, v69, v248
	v_sub_f32_e32 v70, v70, v248
	v_sub_f32_e32 v71, v71, v248
	v_sub_f32_e32 v72, v72, v248
	v_sub_f32_e32 v73, v73, v248
	v_sub_f32_e32 v74, v74, v248
	v_sub_f32_e32 v75, v75, v248
	v_sub_f32_e32 v76, v76, v248
	v_sub_f32_e32 v77, v77, v248
	v_sub_f32_e32 v78, v78, v248
	v_sub_f32_e32 v79, v79, v248
	v_sub_f32_e32 v80, v80, v248
	v_sub_f32_e32 v81, v81, v248
	v_sub_f32_e32 v82, v82, v248
	v_sub_f32_e32 v83, v83, v248
	v_xor_b32_e32 v220, 0x80000000, v248
	v_xor_b32_e32 v221, 0x80000000, v248
	v_xor_b32_e32 v222, 0x80000000, v248
	v_xor_b32_e32 v223, 0x80000000, v248
	v_xor_b32_e32 v224, 0x80000000, v248
	v_xor_b32_e32 v225, 0x80000000, v248
	v_xor_b32_e32 v226, 0x80000000, v248
	v_xor_b32_e32 v227, 0x80000000, v248
	v_xor_b32_e32 v228, 0x80000000, v248
	v_xor_b32_e32 v229, 0x80000000, v248
	v_xor_b32_e32 v230, 0x80000000, v248
	v_xor_b32_e32 v231, 0x80000000, v248
	v_xor_b32_e32 v232, 0x80000000, v248
	v_xor_b32_e32 v233, 0x80000000, v248
	v_xor_b32_e32 v234, 0x80000000, v248
	v_xor_b32_e32 v235, 0x80000000, v248
	s_branch .LcC_back
.LcC_resc:
	v_max_f32_e32 v248, 0, v248
	v_add_f32_e32 v203, v203, v248
	v_exp_f32_e64 v249, -v248
	v_sub_f32_e32 v68, v68, v248
	v_sub_f32_e32 v69, v69, v248
	v_sub_f32_e32 v70, v70, v248
	v_sub_f32_e32 v71, v71, v248
	v_sub_f32_e32 v72, v72, v248
	v_sub_f32_e32 v73, v73, v248
	v_sub_f32_e32 v74, v74, v248
	v_sub_f32_e32 v75, v75, v248
	v_sub_f32_e32 v76, v76, v248
	v_sub_f32_e32 v77, v77, v248
	v_sub_f32_e32 v78, v78, v248
	v_sub_f32_e32 v79, v79, v248
	v_sub_f32_e32 v80, v80, v248
	v_sub_f32_e32 v81, v81, v248
	v_sub_f32_e32 v82, v82, v248
	v_sub_f32_e32 v83, v83, v248
	v_xor_b32_e32 v220, 0x80000000, v203
	v_xor_b32_e32 v221, 0x80000000, v203
	v_xor_b32_e32 v222, 0x80000000, v203
	v_xor_b32_e32 v223, 0x80000000, v203
	v_xor_b32_e32 v224, 0x80000000, v203
	v_xor_b32_e32 v225, 0x80000000, v203
	v_xor_b32_e32 v226, 0x80000000, v203
	v_xor_b32_e32 v227, 0x80000000, v203
	v_xor_b32_e32 v228, 0x80000000, v203
	v_xor_b32_e32 v229, 0x80000000, v203
	v_xor_b32_e32 v230, 0x80000000, v203
	v_xor_b32_e32 v231, 0x80000000, v203
	v_xor_b32_e32 v232, 0x80000000, v203
	v_xor_b32_e32 v233, 0x80000000, v203
	v_xor_b32_e32 v234, 0x80000000, v203
	v_xor_b32_e32 v235, 0x80000000, v203
	v_mul_f32_e32 v4, v249, v4
	v_mul_f32_e32 v5, v249, v5
	v_mul_f32_e32 v6, v249, v6
	v_mul_f32_e32 v7, v249, v7
	v_mul_f32_e32 v8, v249, v8
	v_mul_f32_e32 v9, v249, v9
	v_mul_f32_e32 v10, v249, v10
	v_mul_f32_e32 v11, v249, v11
	v_mul_f32_e32 v12, v249, v12
	v_mul_f32_e32 v13, v249, v13
	v_mul_f32_e32 v14, v249, v14
	v_mul_f32_e32 v15, v249, v15
	v_mul_f32_e32 v16, v249, v16
	v_mul_f32_e32 v17, v249, v17
	v_mul_f32_e32 v18, v249, v18
	v_mul_f32_e32 v19, v249, v19
	v_mul_f32_e32 v20, v249, v20
	v_mul_f32_e32 v21, v249, v21
	v_mul_f32_e32 v22, v249, v22
	v_mul_f32_e32 v23, v249, v23
	v_mul_f32_e32 v24, v249, v24
	v_mul_f32_e32 v25, v249, v25
	v_mul_f32_e32 v26, v249, v26
	v_mul_f32_e32 v27, v249, v27
	v_mul_f32_e32 v28, v249, v28
	v_mul_f32_e32 v29, v249, v29
	v_mul_f32_e32 v30, v249, v30
	v_mul_f32_e32 v31, v249, v31
	v_mul_f32_e32 v32, v249, v32
	v_mul_f32_e32 v33, v249, v33
	v_mul_f32_e32 v34, v249, v34
	v_mul_f32_e32 v35, v249, v35
	v_mul_f32_e32 v36, v249, v36
	v_mul_f32_e32 v37, v249, v37
	v_mul_f32_e32 v38, v249, v38
	v_mul_f32_e32 v39, v249, v39
	v_mul_f32_e32 v40, v249, v40
	v_mul_f32_e32 v41, v249, v41
	v_mul_f32_e32 v42, v249, v42
	v_mul_f32_e32 v43, v249, v43
	v_mul_f32_e32 v44, v249, v44
	v_mul_f32_e32 v45, v249, v45
	v_mul_f32_e32 v46, v249, v46
	v_mul_f32_e32 v47, v249, v47
	v_mul_f32_e32 v48, v249, v48
	v_mul_f32_e32 v49, v249, v49
	v_mul_f32_e32 v50, v249, v50
	v_mul_f32_e32 v51, v249, v51
	v_mul_f32_e32 v52, v249, v52
	v_mul_f32_e32 v53, v249, v53
	v_mul_f32_e32 v54, v249, v54
	v_mul_f32_e32 v55, v249, v55
	v_mul_f32_e32 v56, v249, v56
	v_mul_f32_e32 v57, v249, v57
	v_mul_f32_e32 v58, v249, v58
	v_mul_f32_e32 v59, v249, v59
	v_mul_f32_e32 v60, v249, v60
	v_mul_f32_e32 v61, v249, v61
	v_mul_f32_e32 v62, v249, v62
	v_mul_f32_e32 v63, v249, v63
	v_mul_f32_e32 v64, v249, v64
	v_mul_f32_e32 v65, v249, v65
	v_mul_f32_e32 v66, v249, v66
	v_mul_f32_e32 v67, v249, v67
	v_mul_f32_e32 v204, v249, v204
	s_branch .LcC_back
	s_nop 0
	s_nop 0
	s_nop 0
	s_nop 0
	s_nop 0
	s_nop 0
	s_nop 0
	s_nop 0
	s_nop 0
	s_nop 0
	s_nop 0
	s_nop 0
	s_nop 0
	s_nop 0
	s_nop 0
	s_nop 0
	s_nop 0
	s_nop 0
	s_nop 0
	s_nop 0
	s_nop 0
	s_nop 0
	s_nop 0
	s_nop 0
	s_nop 0
	s_nop 0
	s_nop 0
	s_nop 0
	s_nop 0
	s_nop 0
	s_nop 0
	s_nop 0
	s_nop 0
	s_nop 0
	s_nop 0
	s_nop 0
	s_nop 0
	s_nop 0
	s_nop 0
	s_nop 0
	s_nop 0
	s_nop 0
	s_nop 0
	s_nop 0
	s_nop 0
	s_nop 0
	s_nop 0
	s_nop 0
	s_nop 0
	s_nop 0
	s_nop 0
	s_nop 0
	s_nop 0
	s_nop 0
	s_nop 0
	s_nop 0
	s_nop 0
	s_nop 0
	s_nop 0
	s_nop 0
	s_nop 0
	s_nop 0
	s_nop 0
	s_nop 0
	s_nop 0
	s_nop 0
	s_nop 0
	s_nop 0
	s_nop 0
	s_nop 0
	s_nop 0
	s_nop 0
	s_nop 0
	s_nop 0
	s_nop 0
	s_nop 0
	s_nop 0
	s_nop 0
	s_nop 0
	s_nop 0
	s_nop 0
	s_nop 0
	s_nop 0
	s_nop 0
	s_nop 0
	s_nop 0
	s_nop 0
	s_nop 0
	s_nop 0
	s_nop 0
	s_nop 0
	s_nop 0
	s_nop 0
	s_nop 0
	s_nop 0
	s_nop 0
	s_nop 0
	s_nop 0
	s_nop 0
	s_nop 0
	s_nop 0
	s_nop 0
	s_nop 0
	s_nop 0
	s_nop 0
	s_nop 0
	s_nop 0
	s_nop 0
	s_nop 0
	s_nop 0
	s_nop 0
	s_nop 0
	s_nop 0
	s_nop 0
	s_nop 0
	s_nop 0
	s_nop 0
	s_nop 0
	s_nop 0
	s_nop 0
	s_nop 0
	s_nop 0
	s_nop 0
	s_nop 0
	s_nop 0
	s_nop 0
	s_nop 0
	s_nop 0
	s_nop 0
	s_nop 0
	s_nop 0
	s_nop 0
	s_nop 0
	s_nop 0
	s_nop 0
	s_nop 0
	s_nop 0
	s_nop 0
	s_nop 0
	s_nop 0
	s_nop 0
	s_nop 0
	s_nop 0
	s_nop 0
	s_nop 0
	s_nop 0
	s_nop 0
	s_nop 0
	s_nop 0
	s_nop 0
	s_nop 0
	s_nop 0
	s_nop 0
	s_nop 0
	s_nop 0
	s_nop 0
	s_nop 0
	s_nop 0
	s_nop 0
	s_nop 0
	s_nop 0
	s_nop 0
	s_nop 0
	s_nop 0
	s_nop 0
	s_nop 0
	s_nop 0
	s_nop 0
	s_nop 0
	s_nop 0
	s_nop 0
	s_nop 0
	s_nop 0
	s_nop 0
	s_nop 0
	s_nop 0
	s_nop 0
	s_nop 0
	s_nop 0
	s_nop 0
	s_nop 0
	s_nop 0
	s_nop 0
	s_nop 0
	s_nop 0
	s_nop 0
	s_nop 0
	s_nop 0
	s_nop 0
	s_nop 0
	s_nop 0
	s_nop 0
	s_nop 0
	s_nop 0
	s_nop 0
	s_nop 0
	s_nop 0
	s_nop 0
	s_nop 0
	s_nop 0
	s_nop 0
	s_nop 0
	s_nop 0
	s_nop 0
	s_nop 0
	s_nop 0
	s_nop 0
	s_nop 0
	s_nop 0
	s_nop 0
	s_nop 0
	s_nop 0
	s_nop 0
	s_nop 0
	s_nop 0
	s_nop 0
	s_nop 0
	s_nop 0
	s_nop 0
	s_nop 0
	s_nop 0
	s_nop 0
	s_nop 0
	s_nop 0
	s_nop 0
	s_nop 0
	s_nop 0
	s_nop 0
	s_nop 0
	s_nop 0
	s_nop 0
	s_nop 0
	s_nop 0
	s_nop 0
	s_nop 0
	s_nop 0
	s_nop 0
	s_nop 0
	s_nop 0
	s_nop 0
	s_nop 0
	s_nop 0
	s_nop 0
	s_nop 0
	s_nop 0
	s_nop 0
	s_nop 0
	s_nop 0
	s_nop 0
	s_nop 0
	s_nop 0
	s_nop 0
	s_nop 0
	s_nop 0
	s_nop 0
	s_nop 0
	s_nop 0
	s_nop 0
	s_nop 0
	s_nop 0
	s_nop 0
	s_nop 0
	s_nop 0
	s_nop 0
	s_nop 0
	s_nop 0
	s_nop 0
	s_nop 0
; __device__ __forceinline__ unsigned pk_bf16(float lo, float hi) { f32x2 v = {lo, hi}; bf16x2_t b = __builtin_convertvector(v, bf16x2_t); return __builtin_bit_cast(unsigned, b); }
; __device__ __forceinline__ void attnC_dma(const P2Ctx& C, int b, int h, int qblk) {
;     ...
;     l += __shfl_xor(l, 32);
;     const float inv = 1.0f / l;
;     bf16_t* dst = C.CO + qrow * DM + h * 256 + dvh * 128;
; #pragma unroll
;     for (int cb = 0; cb < 4; ++cb)
; #pragma unroll
;         for (int g = 0; g < 4; ++g) { const int dv0 = 32 * cb + 8 * g + 4 * hi;
;             u32x2 w; w.x = pk_bf16(o[cb][4 * g + 0] * inv, o[cb][4 * g + 1] * inv); w.y = pk_bf16(o[cb][4 * g + 2] * inv, o[cb][4 * g + 3] * inv);
;             *(u32x2*)(dst + dv0) = w; }
;     __syncthreads();
.LcC_epi:
	v_mov_b32_e32 v237, v204
	s_nop 1
	v_permlane32_swap_b32 v237, v204
	v_add_f32_e32 v204, v237, v204
	v_rcp_f32_e32 v204, v204
	v_and_b32_e32 v236, 31, v219
	v_lshlrev_b32_e32 v236, 11, v236
	v_lshrrev_b32_e32 v237, 5, v219
	v_lshl_add_u32 v236, v237, 3, v236
	s_nop 7
	s_nop 3
	v_mul_f32_e32 v4, v4, v204
	v_mul_f32_e32 v5, v5, v204
	v_mul_f32_e32 v6, v6, v204
	v_mul_f32_e32 v7, v7, v204
	v_cvt_pk_bf16_f32 v68, v4, v5
	v_cvt_pk_bf16_f32 v69, v6, v7
	global_store_dwordx2 v236, v[68:69], s[22:23] offset:0
	v_mul_f32_e32 v8, v8, v204
	v_mul_f32_e32 v9, v9, v204
	v_mul_f32_e32 v10, v10, v204
	v_mul_f32_e32 v11, v11, v204
	v_cvt_pk_bf16_f32 v70, v8, v9
	v_cvt_pk_bf16_f32 v71, v10, v11
	global_store_dwordx2 v236, v[70:71], s[22:23] offset:16
	v_mul_f32_e32 v12, v12, v204
	v_mul_f32_e32 v13, v13, v204
	v_mul_f32_e32 v14, v14, v204
	v_mul_f32_e32 v15, v15, v204
	v_cvt_pk_bf16_f32 v68, v12, v13
	v_cvt_pk_bf16_f32 v69, v14, v15
	global_store_dwordx2 v236, v[68:69], s[22:23] offset:32
	v_mul_f32_e32 v16, v16, v204
	v_mul_f32_e32 v17, v17, v204
	v_mul_f32_e32 v18, v18, v204
	v_mul_f32_e32 v19, v19, v204
	v_cvt_pk_bf16_f32 v70, v16, v17
	v_cvt_pk_bf16_f32 v71, v18, v19
	global_store_dwordx2 v236, v[70:71], s[22:23] offset:48
	v_mul_f32_e32 v20, v20, v204
	v_mul_f32_e32 v21, v21, v204
	v_mul_f32_e32 v22, v22, v204
	v_mul_f32_e32 v23, v23, v204
	v_cvt_pk_bf16_f32 v68, v20, v21
	v_cvt_pk_bf16_f32 v69, v22, v23
	global_store_dwordx2 v236, v[68:69], s[22:23] offset:64
	v_mul_f32_e32 v24, v24, v204
	v_mul_f32_e32 v25, v25, v204
	v_mul_f32_e32 v26, v26, v204
	v_mul_f32_e32 v27, v27, v204
	v_cvt_pk_bf16_f32 v70, v24, v25
	v_cvt_pk_bf16_f32 v71, v26, v27
	global_store_dwordx2 v236, v[70:71], s[22:23] offset:80
	v_mul_f32_e32 v28, v28, v204
	v_mul_f32_e32 v29, v29, v204
	v_mul_f32_e32 v30, v30, v204
	v_mul_f32_e32 v31, v31, v204
	v_cvt_pk_bf16_f32 v68, v28, v29
	v_cvt_pk_bf16_f32 v69, v30, v31
	global_store_dwordx2 v236, v[68:69], s[22:23] offset:96
	v_mul_f32_e32 v32, v32, v204
	v_mul_f32_e32 v33, v33, v204
	v_mul_f32_e32 v34, v34, v204
	v_mul_f32_e32 v35, v35, v204
	v_cvt_pk_bf16_f32 v70, v32, v33
	v_cvt_pk_bf16_f32 v71, v34, v35
	global_store_dwordx2 v236, v[70:71], s[22:23] offset:112
	v_mul_f32_e32 v36, v36, v204
	v_mul_f32_e32 v37, v37, v204
	v_mul_f32_e32 v38, v38, v204
	v_mul_f32_e32 v39, v39, v204
	v_cvt_pk_bf16_f32 v68, v36, v37
	v_cvt_pk_bf16_f32 v69, v38, v39
	global_store_dwordx2 v236, v[68:69], s[22:23] offset:128
	v_mul_f32_e32 v40, v40, v204
	v_mul_f32_e32 v41, v41, v204
	v_mul_f32_e32 v42, v42, v204
	v_mul_f32_e32 v43, v43, v204
	v_cvt_pk_bf16_f32 v70, v40, v41
	v_cvt_pk_bf16_f32 v71, v42, v43
	global_store_dwordx2 v236, v[70:71], s[22:23] offset:144
	v_mul_f32_e32 v44, v44, v204
	v_mul_f32_e32 v45, v45, v204
	v_mul_f32_e32 v46, v46, v204
	v_mul_f32_e32 v47, v47, v204
	v_cvt_pk_bf16_f32 v68, v44, v45
	v_cvt_pk_bf16_f32 v69, v46, v47
	global_store_dwordx2 v236, v[68:69], s[22:23] offset:160
	v_mul_f32_e32 v48, v48, v204
	v_mul_f32_e32 v49, v49, v204
	v_mul_f32_e32 v50, v50, v204
	v_mul_f32_e32 v51, v51, v204
	v_cvt_pk_bf16_f32 v70, v48, v49
	v_cvt_pk_bf16_f32 v71, v50, v51
	global_store_dwordx2 v236, v[70:71], s[22:23] offset:176
	v_mul_f32_e32 v52, v52, v204
	v_mul_f32_e32 v53, v53, v204
	v_mul_f32_e32 v54, v54, v204
	v_mul_f32_e32 v55, v55, v204
	v_cvt_pk_bf16_f32 v68, v52, v53
	v_cvt_pk_bf16_f32 v69, v54, v55
	global_store_dwordx2 v236, v[68:69], s[22:23] offset:192
	v_mul_f32_e32 v56, v56, v204
	v_mul_f32_e32 v57, v57, v204
	v_mul_f32_e32 v58, v58, v204
	v_mul_f32_e32 v59, v59, v204
	v_cvt_pk_bf16_f32 v70, v56, v57
	v_cvt_pk_bf16_f32 v71, v58, v59
	global_store_dwordx2 v236, v[70:71], s[22:23] offset:208
	v_mul_f32_e32 v60, v60, v204
	v_mul_f32_e32 v61, v61, v204
	v_mul_f32_e32 v62, v62, v204
	v_mul_f32_e32 v63, v63, v204
	v_cvt_pk_bf16_f32 v68, v60, v61
	v_cvt_pk_bf16_f32 v69, v62, v63
	global_store_dwordx2 v236, v[68:69], s[22:23] offset:224
	v_mul_f32_e32 v64, v64, v204
	v_mul_f32_e32 v65, v65, v204
	v_mul_f32_e32 v66, v66, v204
	v_mul_f32_e32 v67, v67, v204
	v_cvt_pk_bf16_f32 v70, v64, v65
	v_cvt_pk_bf16_f32 v71, v66, v67
	global_store_dwordx2 v236, v[70:71], s[22:23] offset:240
	s_waitcnt vmcnt(0)
	s_barrier
